# speedup vs baseline: 1.0102x; 1.0051x over previous
; #define BAR __builtin_amdgcn_s_barrier()
; #define TILE_PREFETCH(brow_, bcol_, par_) do { \
;     STAGE(SB(0, 0), Bt, bcol_, 0); STAGE(SA(0, 0), A, brow_, 0); \
;     STAGE(SB(0, 1), Bt, (bcol_) + HALF, 0); STAGE(SA(0, 1), A, (brow_) + HALF, 0); \
;     STAGE(SB(1, 0), Bt, bcol_, 1); STAGE(SA(1, 0), A, brow_, 1); STAGE(SB(1, 1), Bt, (bcol_) + HALF, 1); } while (0)
; #define SINV_ISSUE(valid_, brow_) do { if (mode != EPI_RES && (valid_)) { \
;       _Pragma("unroll") for (int i = 0; i < 16; ++i) pv[i] = p->rowss[(size_t)((tid >> 8) * 16 + i) * S_ + (brow_) + (tid & 255)]; \
;     } else { _Pragma("unroll") for (int i = 0; i < 16; ++i) pv[i] = 0.f; } } while (0)
; #define SINV_COMMIT(par_) do { if (mode != EPI_RES) { \
;       float ss = 0.f; \
;       _Pragma("unroll") for (int i = 0; i < 16; ++i) ss += pv[i]; \
;       s_inv[(par_) * 512 + tid] = ss; \
;     } } while (0)
; __device__ __forceinline__ void gemm_phase(KP p, char* shmc, const u16* __restrict__ A,
;                                            const u16* __restrict__ Bt, const int N, const int K, const int mode,
;                                            const float* __restrict__ xin, const float resw) {
;     ...
;     if (wr == 0) BAR;
;     const int ntix = tix + gridDim.x;
;     int nbrow = 0, nbcol = 0, npn = 0;
;     if (ntix < nwg) {
;       TILE_MAP(ntix, nbrow, nbcol, npn);
;       TILE_PREFETCH(nbrow, nbcol, par ^ 1);
;     }
;     float pv[16];
;     SINV_ISSUE(ntix < nwg, nbrow);
;     epilogue(p, acc, s_inv + par * 512, mode, xin, resw, brow, bcol, pn);
;     SINV_COMMIT(par ^ 1);
;     tix = ntix; brow = nbrow; bcol = nbcol; pn = npn; par ^= 1;
.Lmy_kloop_sw_end:
.Lmy_join:
	s_mov_b32 s26, s43
	s_mov_b32 s45, s46
	s_mov_b32 s44, s47
	s_cmp_ge_i32 s66, s51
	s_cselect_b64 s[6:7], -1, 0
